# attention: one static s_setprio 1 for waves 0-3 at phase entry, per-QK priority flips deleted (section 7.4 lever, older half measured better than younger)
# speedup vs baseline: 1.0089x; 1.0089x over previous
; #define LAS __attribute__((address_space(3)))
; __device__ __forceinline__ void attention_phase(const KP& p, LAS unsigned char* lds, unsigned char* ws, int rep) {
;     int tid_l = threadIdx.x; asm volatile("" : "+v"(tid_l));
;     const int tid0 = tid_l;
;     const int xcd = blockIdx.x & 7;
;     unsigned* const cbase = (unsigned*)(ws + WS_CTL) + (rep * 8) * 64;
;     LAS unsigned* wq = (LAS unsigned*)(lds + LDS_STAGE);
;     const float lam = __expf(wave_sum(p.lq1[tid0 & 63] * p.lk1[tid0 & 63])) - __expf(wave_sum(p.lq2[tid0 & 63] * p.lk2[tid0 & 63])) + p.lam_init;
.LBB0_39:
	s_andn2_b64 vcc, exec, s[6:7]
	s_cbranch_vccnz .LBB0_169
	v_mov_b32_e32 v236, v216
	v_readfirstlane_b32 s40, v216
	s_bitcmp1_b32 s40, 8
	s_cbranch_scc1 .Lprio_young_done
	s_setprio 1
.Lprio_young_done:
	v_readlane_b32 s40, v253, 17
	v_and_b32_e32 v0, 63, v236
	v_lshlrev_b32_e32 v0, 2, v0
	v_readlane_b32 s52, v253, 29
	v_readlane_b32 s53, v253, 30
	v_readlane_b32 s54, v253, 31
	v_readlane_b32 s55, v253, 32
	s_nop 2
	global_load_dword v2, v0, s[52:53]
	s_waitcnt lgkmcnt(0)
	global_load_dword v3, v0, s[54:55]
	global_load_dword v4, v0, s[72:73]
	s_nop 0
	global_load_dword v0, v0, s[74:75]
	v_and_b32_e32 v5, 64, v219
	v_xor_b32_e32 v6, 1, v219
	v_add_u32_e32 v5, 64, v5
	v_xor_b32_e32 v7, 2, v219
	v_cmp_lt_i32_e32 vcc, v6, v5
	v_xor_b32_e32 v8, 4, v219
	v_xor_b32_e32 v9, 8, v219
	v_cndmask_b32_e32 v6, v219, v6, vcc
	v_cmp_lt_i32_e32 vcc, v7, v5
	v_xor_b32_e32 v10, 16, v219
	v_xor_b32_e32 v11, 32, v219
	v_cndmask_b32_e32 v7, v219, v7, vcc
	v_cmp_lt_i32_e32 vcc, v8, v5
	v_lshlrev_b32_e32 v6, 2, v6
	v_lshlrev_b32_e32 v7, 2, v7
	v_cndmask_b32_e32 v8, v219, v8, vcc
	v_cmp_lt_i32_e32 vcc, v9, v5
	v_lshlrev_b32_e32 v8, 2, v8
	s_lshl_b64 s[6:7], s[8:9], 2
	v_cndmask_b32_e32 v9, v219, v9, vcc
	v_cmp_lt_i32_e32 vcc, v10, v5
	s_add_u32 s36, s10, s6
	s_addc_u32 s58, s11, s7
	v_cndmask_b32_e32 v10, v219, v10, vcc
	v_cmp_lt_i32_e32 vcc, v11, v5
	s_add_u32 s8, s10, 0x8000
	s_addc_u32 s9, s11, 0
	v_cndmask_b32_e32 v5, v219, v11, vcc
	v_lshlrev_b32_e32 v5, 2, v5
	s_add_u32 s12, s10, 0xba00000
	s_addc_u32 s13, s11, 0
	s_add_u32 s59, s10, 0x9800000
	s_addc_u32 s60, s11, 0
	s_add_u32 s61, s10, 0xb800000
	s_addc_u32 s62, s11, 0
	s_add_u32 s63, s10, 0xea00000
	s_addc_u32 s64, s11, 0
	v_readlane_b32 s41, v253, 18
	s_add_u32 s40, s10, 0x13000000
	s_addc_u32 s41, s11, 0
	s_add_u32 s65, s10, 0x15000000
	s_addc_u32 s67, s11, 0
	s_add_u32 s68, s10, 0x10a00000
	s_mov_b32 s2, 0
	v_cmp_eq_u32_e64 s[38:39], 0, v236
	s_addc_u32 s69, s11, 0
	v_readlane_b32 s42, v253, 19
	v_readlane_b32 s43, v253, 20
	v_readlane_b32 s44, v253, 21
	v_readlane_b32 s45, v253, 22
	v_readlane_b32 s46, v253, 23
	v_readlane_b32 s47, v253, 24
	v_readlane_b32 s48, v253, 25
	v_readlane_b32 s49, v253, 26
	v_readlane_b32 s50, v253, 27
	v_readlane_b32 s51, v253, 28
	s_waitcnt vmcnt(0)
	v_mul_f32_e32 v11, v2, v3
	ds_bpermute_b32 v11, v6, v11
	s_waitcnt vmcnt(0)
	v_mul_f32_e32 v12, v4, v0
	ds_bpermute_b32 v6, v6, v12
	s_waitcnt lgkmcnt(1)
	v_fmac_f32_e32 v11, v2, v3
	v_lshlrev_b32_e32 v3, 2, v9
	s_waitcnt lgkmcnt(0)
	v_fmac_f32_e32 v6, v4, v0
	ds_bpermute_b32 v0, v7, v11
	ds_bpermute_b32 v2, v7, v6
	v_lshlrev_b32_e32 v4, 2, v10
	s_waitcnt lgkmcnt(1)
	v_add_f32_e32 v0, v11, v0
	s_waitcnt lgkmcnt(0)
	v_add_f32_e32 v2, v6, v2
	ds_bpermute_b32 v6, v8, v0
	ds_bpermute_b32 v7, v8, v2
	s_waitcnt lgkmcnt(1)
	v_add_f32_e32 v0, v0, v6
	s_waitcnt lgkmcnt(0)
	v_add_f32_e32 v2, v2, v7
	ds_bpermute_b32 v6, v3, v0
	ds_bpermute_b32 v3, v3, v2
	s_waitcnt lgkmcnt(1)
	v_add_f32_e32 v0, v0, v6
	s_waitcnt lgkmcnt(0)
	v_add_f32_e32 v2, v2, v3
	ds_bpermute_b32 v3, v4, v0
	ds_bpermute_b32 v4, v4, v2
	s_waitcnt lgkmcnt(1)
	v_add_f32_e32 v0, v0, v3
	s_waitcnt lgkmcnt(0)
	v_add_f32_e32 v2, v2, v4
	ds_bpermute_b32 v3, v5, v0
	ds_bpermute_b32 v4, v5, v2
	s_waitcnt lgkmcnt(1)
	v_add_f32_e32 v0, v0, v3
	s_waitcnt lgkmcnt(0)
	v_add_f32_e32 v2, v2, v4
	v_mul_f32_e32 v0, 0x3fb8aa3b, v0
	v_mul_f32_e32 v2, 0x3fb8aa3b, v2
	v_exp_f32_e32 v0, v0
	v_exp_f32_e32 v2, v2
	s_nop 0
	v_sub_f32_e32 v0, v0, v2
	v_add_f32_e32 v237, s86, v0
	s_branch .LBB0_42

; template <int DQK, int DV, bool MLA>
; __device__ __forceinline__ void attn_pass(LAS unsigned char* lds, const bf16_t* Qrow, const bf16_t* K0, int pitchK, const bf16_t* KrB, const bf16_t* Vt0, int NT, int q0w,
;                                           f32x16 (&o)[DV / 32], float& l_out, int tid) {
;     ...
;     bf16x8 q[ND];
; #pragma unroll
;     for (int d0 = 0; d0 < ND; ++d0) q[d0] = *(const GAS bf16x8*)(Qrow + 16 * d0 + 8 * hi);
; #pragma unroll
;     for (int d = 0; d < NDV; ++d)
; #pragma unroll
;         for (int r = 0; r < 16; ++r) o[d][r] = 0.f;
;     float m = 0.f, l = 0.f;
;     f32x16 negm;
; #pragma unroll
;     for (int r = 0; r < 16; ++r) negm[r] = 0.f;
; #pragma unroll
;     for (int d0 = 0; d0 < ND; ++d0) asm volatile("" : "+v"(q[d0]));
;     const bf16_t* ksrc; const bf16_t* rsrc = nullptr; const bf16_t* vsrc[NVC];
;     { const int row = 8 * wid + (lane >> 3), c = (lane & 7) ^ ((row >> 1) & 7); ksrc = K0 + (size_t)row * pitchK + c * 8; }
;     if (MLA) { const int row = 16 * (wid & 3) + (lane >> 2), c = (lane & 3) ^ ((row >> 2) & 3); rsrc = KrB + (size_t)row * 32 + c * 8; }
; #pragma unroll
;     for (int j = 0; j < NVC; ++j) { const int row = 8 * (wid + 8 * j) + (lane >> 3), c = (lane & 7) ^ ((row >> 1) & 7); vsrc[j] = Vt0 + (size_t)row * 64 + c * 8; }
;     ...
;     const int xs = (r32 >> 1) & 7;
;     const int yk = (xs ^ hi) << 4;
;     const int yr = (((r32 >> 2) & 3) ^ hi) << 4;
;     bf16x8 kf[2 * ND];
;     ...
;     ATT_DMA_K(0, 0); ATT_DMA_V(0, 0); ATT_DMA_K(1, 1); ATT_DMA_V(1, 1); ATT_DMA_K(2, 2);
;     asm volatile("s_waitcnt vmcnt(0)" ::: "memory");
;     __builtin_amdgcn_s_barrier();
;     asm volatile("" ::: "memory");
;     ATT_KLOAD(0);
; __device__ __forceinline__ void attention_phase(const KP& p, LAS unsigned char* lds, unsigned char* ws, int rep) {
;     ...
;         if (tid0 == 0) *wq = atomicAdd(counter, 1u);
;         __syncthreads();
;         const unsigned u = *wq;
;         __syncthreads();
;         if (u >= (unsigned)(NUNITS / 8)) break;
;         int tid = tid_l; asm volatile("" : "+v"(tid));
;         const int lane = tid & 63, r32 = lane & 31, hi = lane >> 5, wid = tid >> 6;
;         const int code = ((const int*)(ws + WS_CTL + 32768))[u];
;         const int qb = code >> 3, sidx = code & 7;
;         const int w = sidx < 2 ? 2 * qx + sidx : 16 + 4 * qx + (sidx - 2);
;         const int NT = 4 * (qb + 1), q0w = qb * 256 + wid * 32;
.LBB0_51:
	s_or_b64 exec, exec, s[6:7]
	v_mov_b32_e32 v0, s3
	s_waitcnt lgkmcnt(0)
	s_barrier
	ds_read_b32 v0, v0
	s_movk_i32 s6, 0xbf
	s_waitcnt lgkmcnt(0)
	s_barrier
	v_cmp_lt_u32_e32 vcc, s6, v0
	s_mov_b64 s[6:7], -1
	s_cbranch_vccnz .LBB0_46
	v_lshlrev_b64 v[2:3], 2, v[0:1]
	v_mov_b32_e32 v240, v236
	v_lshl_add_u64 v[2:3], s[8:9], 0, v[2:3]
	global_load_dword v0, v[2:3], off
	v_ashrrev_i32_e32 v2, 1, v240
	v_and_b32_e32 v2, 0xffffffe0, v2
	v_and_b32_e32 v242, 31, v240
	v_bfe_u32 v239, v240, 5, 1
	v_lshrrev_b32_e32 v3, 1, v240
	v_bfe_u32 v241, v240, 3, 3
	v_lshlrev_b32_e32 v238, 7, v242
	v_bitop3_b32 v243, v3, v239, 7 bitop3:0x6c
	s_waitcnt vmcnt(0)
	v_readfirstlane_b32 s14, v0
	s_ashr_i32 s52, s14, 3
	s_and_b32 s14, s14, 7
	s_cmp_lt_u32 s14, 2
	s_cselect_b32 s53, s71, s70
	s_lshl_b32 s89, s52, 2
	v_lshl_add_u32 v202, s52, 8, v2
	s_add_i32 s53, s53, s14
	s_add_i32 s88, s89, 4
	v_ashrrev_i32_e32 v203, 31, v202
	s_cmp_gt_u32 s53, 15
	v_lshlrev_b32_e32 v0, 4, v239
	s_cbranch_scc0 .LBB0_92
	s_add_i32 s6, s53, -16
	s_lshr_b32 s16, s6, 3
	s_lshl_b64 s[44:45], s[16:17], 13
	v_lshl_add_u64 v[204:205], s[44:45], 0, v[202:203]
	v_or_b32_e32 v204, v204, v242
	v_mov_b64_e32 v[2:3], s[12:13]
	s_and_b32 s54, s53, 7
	v_mad_u64_u32 v[2:3], s[44:45], v204, s33, v[2:3]
	v_mad_i32_i24 v3, v205, s33, v3
	s_mul_i32 s44, s54, 0xc0
	s_mov_b32 s45, s17
	v_lshl_add_u64 v[2:3], v[2:3], 0, s[44:45]
	v_lshl_add_u64 v[2:3], v[2:3], 0, v[0:1]
	global_load_dwordx4 v[82:85], v[2:3], off
	global_load_dwordx4 v[86:89], v[2:3], off offset:32
	global_load_dwordx4 v[90:93], v[2:3], off offset:64
	global_load_dwordx4 v[94:97], v[2:3], off offset:96
	global_load_dwordx4 v[98:101], v[2:3], off offset:128
	global_load_dwordx4 v[102:105], v[2:3], off offset:160
	s_lshl_b64 s[6:7], s[16:17], 19
	s_add_u32 s14, s61, s6
	s_addc_u32 s15, s62, s7
	s_lshl_b32 s6, s16, 7
	s_mov_b32 s7, s17
	s_lshl_b64 s[6:7], s[6:7], 16
	s_add_u32 s6, s63, s6
	s_addc_u32 s7, s64, s7
	s_lshl_b32 s46, s54, 13
	s_add_u32 s6, s6, s46
	s_addc_u32 s7, s7, 0
	s_lshl_b64 s[44:45], s[16:17], 23
	s_add_u32 s16, s59, s44
	s_addc_u32 s45, s60, s45
	s_lshl_b32 s44, s54, 7
	s_add_u32 s44, s16, s44
	v_readfirstlane_b32 s16, v240
	s_addc_u32 s45, s45, 0
	s_ashr_i32 s16, s16, 6
	v_lshl_or_b32 v2, s16, 3, v241
	v_lshrrev_b32_e32 v3, 1, v2
	v_xor_b32_e32 v6, v3, v240
	v_ashrrev_i32_e32 v3, 31, v2
	v_lshlrev_b64 v[4:5], 10, v[2:3]
	v_lshlrev_b32_e32 v6, 4, v6
	v_lshl_add_u64 v[4:5], s[44:45], 0, v[4:5]
	v_and_b32_e32 v6, 0x70, v6
	v_mov_b32_e32 v7, v1
	v_lshl_add_u64 v[50:51], v[4:5], 0, v[6:7]
	v_lshrrev_b32_e32 v4, 4, v240
	v_xor_b32_e32 v8, v4, v240
	v_lshlrev_b32_e32 v4, 4, v240
	s_lshl_b32 s16, s16, 10
	v_and_b32_e32 v4, 0x3c0, v4
	s_and_b32 s44, s16, 0xc00
	v_or_b32_e32 v4, s44, v4
	v_mov_b32_e32 v5, v1
	v_lshlrev_b32_e32 v8, 4, v8
	v_lshl_add_u64 v[4:5], s[14:15], 0, v[4:5]
	v_and_b32_e32 v8, 48, v8
	v_mov_b32_e32 v9, v1
	v_lshl_add_u64 v[52:53], v[4:5], 0, v[8:9]
	v_lshl_add_u64 v[4:5], s[6:7], 0, v[6:7]
	s_add_i32 s16, s16, 0
	v_lshlrev_b64 v[2:3], 7, v[2:3]
	v_lshl_add_u64 v[54:55], v[4:5], 0, v[2:3]
	s_add_i32 s56, s16, 0xc000
	v_lshl_add_u64 v[2:3], v[50:51], 0, s[18:19]
	v_lshlrev_b32_e32 v244, 4, v243
	s_mov_b32 s6, m0
	s_mov_b32 m0, s16
	s_nop 0
	global_load_lds_dwordx4 v[50:51], off
	s_mov_b32 m0, s6
	s_add_i32 s6, s44, 0
	s_add_i32 s55, s6, 0x8000
	s_mov_b32 s7, m0
	s_mov_b32 m0, s55
	s_nop 0
	global_load_lds_dwordx4 v[52:53], off
	s_mov_b32 m0, s7
	s_nop 0
	s_mov_b32 s7, m0
	s_mov_b32 m0, s56
	s_nop 0
	global_load_lds_dwordx4 v[54:55], off
	s_mov_b32 m0, s7
	s_add_i32 s7, s16, 0x2000
	s_mov_b32 s14, m0
	s_mov_b32 m0, s7
	s_nop 0
	global_load_lds_dwordx4 v[2:3], off
	s_mov_b32 m0, s14
	v_lshl_add_u64 v[2:3], v[52:53], 0, s[20:21]
	s_add_i32 s7, s6, 0x9000
	s_mov_b32 s14, m0
	s_mov_b32 m0, s7
	s_nop 0
	global_load_lds_dwordx4 v[2:3], off
	s_mov_b32 m0, s14
	v_lshl_add_u64 v[2:3], v[54:55], 0, s[18:19]
	s_add_i32 s7, s16, 0xe000
	s_mov_b32 s14, m0
	s_mov_b32 m0, s7
	s_nop 0
	global_load_lds_dwordx4 v[2:3], off
	s_mov_b32 m0, s14
	v_lshl_add_u64 v[2:3], v[50:51], 0, s[22:23]
	s_add_i32 s7, s16, 0x4000
	s_mov_b32 s14, m0
	s_mov_b32 m0, s7
	s_nop 0
	global_load_lds_dwordx4 v[2:3], off
	s_mov_b32 m0, s14
	v_lshl_add_u64 v[2:3], v[52:53], 0, s[24:25]
	s_add_i32 s7, s6, 0xa000
	s_mov_b32 s14, m0
	s_mov_b32 m0, s7
	s_nop 0
	global_load_lds_dwordx4 v[2:3], off
	s_mov_b32 m0, s14
	s_waitcnt vmcnt(0)
	s_barrier
	s_cmp_lt_i32 s52, 0
	s_cbranch_scc1 .LBB0_166
	v_lshrrev_b32_e32 v2, 2, v240
	v_bitop3_b32 v2, v2, v239, 3 bitop3:0x6c
	v_lshlrev_b32_e32 v245, 4, v2
	v_add_u32_e32 v246, 0, v238
	v_lshlrev_b32_e32 v56, 6, v242
	v_sub_u32_e32 v247, v246, v56
	v_xor_b32_e32 v248, 32, v245
	v_xor_b32_e32 v249, 0x60, v244
	v_xor_b32_e32 v250, 64, v244
	v_xor_b32_e32 v251, 32, v244
	v_add_u32_e32 v57, v247, v248
	v_add_u32_e32 v58, v247, v245
	v_add_u32_e32 v59, v246, v249
	v_add_u32_e32 v60, v246, v250
	v_add_u32_e32 v61, v246, v251
	v_add_u32_e32 v62, v246, v244
	ds_read_b128 v[106:109], v57 offset:34816
	ds_read_b128 v[118:121], v57 offset:32768
	ds_read_b128 v[110:113], v58 offset:34816
	ds_read_b128 v[114:117], v58 offset:32768
	ds_read_b128 v[122:125], v59 offset:4096
	ds_read_b128 v[126:129], v59
	ds_read_b128 v[130:133], v60 offset:4096
	ds_read_b128 v[134:137], v60
	ds_read_b128 v[138:141], v61 offset:4096
	ds_read_b128 v[142:145], v61
	ds_read_b128 v[146:149], v62 offset:4096
	ds_read_b128 v[150:153], v62
	v_lshl_add_u64 v[2:3], v[50:51], 0, s[26:27]
	s_add_i32 s7, s16, 0x6000
	s_mov_b32 s14, m0
	s_mov_b32 m0, s7
	s_nop 0
	global_load_lds_dwordx4 v[2:3], off
	s_mov_b32 m0, s14
	s_mov_b64 s[14:15], 0x3000
	v_lshl_add_u64 v[2:3], v[52:53], 0, s[14:15]
	s_add_i32 s6, s6, 0xb000
	s_mov_b32 s7, m0
	s_mov_b32 m0, s6
	s_nop 0
	global_load_lds_dwordx4 v[2:3], off
	s_mov_b32 m0, s7
	v_lshl_add_u64 v[2:3], v[54:55], 0, s[22:23]
	s_add_i32 s6, s16, 0x10000
	s_mov_b32 s7, m0
	s_mov_b32 m0, s6
	s_nop 0
	global_load_lds_dwordx4 v[2:3], off
	s_mov_b32 m0, s7
	v_mov_b32_e32 v34, v1
	v_mov_b32_e32 v35, v1
	v_mov_b32_e32 v36, v1
	v_mov_b32_e32 v37, v1
	v_mov_b32_e32 v38, v1
	v_mov_b32_e32 v39, v1
	v_mov_b32_e32 v40, v1
	v_mov_b32_e32 v41, v1
	v_mov_b32_e32 v42, v1
	v_mov_b32_e32 v43, v1
	v_mov_b32_e32 v44, v1
	v_mov_b32_e32 v45, v1
	v_mov_b32_e32 v46, v1
	v_mov_b32_e32 v47, v1
	v_mov_b32_e32 v48, v1
	v_mov_b32_e32 v49, v1
	v_mov_b64_e32 v[2:3], v[34:35]
	v_or_b32_e32 v252, v202, v242
	v_cmp_lt_i32_e64 s[48:49], -1, v202
	v_mov_b32_e32 v207, 0
	v_mov_b32_e32 v206, 0
	v_mov_b64_e32 v[4:5], v[36:37]
	v_mov_b64_e32 v[6:7], v[38:39]
	v_mov_b64_e32 v[8:9], v[40:41]
	v_mov_b64_e32 v[10:11], v[42:43]
	v_mov_b64_e32 v[12:13], v[44:45]
	v_mov_b64_e32 v[14:15], v[46:47]
	v_mov_b64_e32 v[16:17], v[48:49]
	s_and_saveexec_b64 s[44:45], s[48:49]
	s_cbranch_execz .LBB0_58
; #define MFMA32(a, b, c) __builtin_amdgcn_mfma_f32_32x32x16_bf16((a), (b), (c), 0, 0, 0)
; #define PV_IDX(g) (((g) & 1) * 4 + PV_KS(g))
; template <int DQK, int DV, bool MLA>
; __device__ __forceinline__ void attn_pass(LAS unsigned char* lds, const bf16_t* Qrow, const bf16_t* K0, int pitchK, const bf16_t* KrB, const bf16_t* Vt0, int NT, int q0w,
;                                           f32x16 (&o)[DV / 32], float& l_out, int tid) {
;     ...
;             __builtin_amdgcn_s_setprio(1);
; #pragma unroll
;             for (int d0 = 0; d0 < ND; ++d0) { s0 = MFMA32(kf[2 * d0], q[d0], s0); s1 = MFMA32(kf[2 * d0 + 1], q[d0], s1); }
;             __builtin_amdgcn_s_setprio(0);
;             __builtin_amdgcn_sched_barrier(0);
;             if (t + 1 < NT) ATT_KLOAD((t + 1) & 3);
;             bf16x8 vf[8];
;             if (pend) {
; #pragma unroll
;                 for (int g = 0; g < 8; ++g) vf[PV_IDX(g)] = VFRAG(vp, PV_D(g), PV_KS(g));
;             }
;             __builtin_amdgcn_sched_barrier(0);
;             if (64 * t + 63 > q0w) {
;                 int hi_l = hi; asm volatile("" : "+v"(hi_l));
;                 const int qrow = q0w + r32, kb0 = 64 * t + 4 * hi_l;
; #pragma unroll
;                 for (int r = 0; r < 16; ++r) { const int kv = kb0 + (r & 3) + 8 * (r >> 2); if (kv > qrow) s0[r] = -INFINITY; if (kv + 32 > qrow) s1[r] = -INFINITY; }
;             }
	s_waitcnt lgkmcnt(0)
	v_mfma_f32_32x32x16_bf16 v[18:33], v[150:153], v[82:85], 0
	v_mfma_f32_32x32x16_bf16 v[2:17], v[146:149], v[82:85], 0
	v_mfma_f32_32x32x16_bf16 v[18:33], v[142:145], v[86:89], v[18:33]
	v_mfma_f32_32x32x16_bf16 v[2:17], v[138:141], v[86:89], v[2:17]
	v_mfma_f32_32x32x16_bf16 v[18:33], v[134:137], v[90:93], v[18:33]
	v_mfma_f32_32x32x16_bf16 v[2:17], v[130:133], v[90:93], v[2:17]
	v_mfma_f32_32x32x16_bf16 v[18:33], v[126:129], v[94:97], v[18:33]
	v_mfma_f32_32x32x16_bf16 v[2:17], v[122:125], v[94:97], v[2:17]
	v_mfma_f32_32x32x16_bf16 v[18:33], v[114:117], v[98:101], v[18:33]
	v_mfma_f32_32x32x16_bf16 v[2:17], v[110:113], v[98:101], v[2:17]
	v_mfma_f32_32x32x16_bf16 v[18:33], v[118:121], v[102:105], v[18:33]
	v_mfma_f32_32x32x16_bf16 v[2:17], v[106:109], v[102:105], v[2:17]
	ds_read_b128 v[150:153], v62 offset:8192
	ds_read_b128 v[146:149], v62 offset:12288
	ds_read_b128 v[142:145], v61 offset:8192
	ds_read_b128 v[138:141], v61 offset:12288
	ds_read_b128 v[134:137], v60 offset:8192
	ds_read_b128 v[130:133], v60 offset:12288
	ds_read_b128 v[126:129], v59 offset:8192
	ds_read_b128 v[122:125], v59 offset:12288
	ds_read_b128 v[114:117], v58 offset:36864
	ds_read_b128 v[110:113], v58 offset:38912
	ds_read_b128 v[106:109], v57 offset:38912
	ds_read_b128 v[118:121], v57 offset:36864
	v_cmp_gt_u32_e32 vcc, 63, v202
	s_and_saveexec_b64 s[6:7], vcc
	s_cbranch_execz .LBB0_57
	v_mov_b32_e32 v34, v239
	s_nop 0
	v_lshlrev_b32_e32 v34, 2, v34
	v_add_u32_e32 v35, 32, v34
	v_cmp_le_i32_e32 vcc, v35, v252
	v_add_u32_e32 v35, 33, v34
	s_nop 0
	v_cndmask_b32_e32 v2, v220, v2, vcc
	v_cmp_lt_i32_e32 vcc, v34, v252
	s_nop 1
	v_cndmask_b32_e32 v19, v220, v19, vcc
	v_cmp_le_i32_e32 vcc, v34, v252
	s_nop 1
	v_cndmask_b32_e32 v18, v220, v18, vcc
	v_cmp_le_i32_e32 vcc, v35, v252
	v_or_b32_e32 v35, 2, v34
	s_nop 0
	v_cndmask_b32_e32 v3, v220, v3, vcc
	v_cmp_le_i32_e32 vcc, v35, v252
	v_add_u32_e32 v35, 34, v34
	s_nop 0
	v_cndmask_b32_e32 v20, v220, v20, vcc
	v_cmp_le_i32_e32 vcc, v35, v252
	v_or_b32_e32 v35, 3, v34
	s_nop 0
	v_cndmask_b32_e32 v4, v220, v4, vcc
	v_cmp_le_i32_e32 vcc, v35, v252
	v_add_u32_e32 v35, 35, v34
	s_nop 0
	v_cndmask_b32_e32 v21, v220, v21, vcc
	v_cmp_le_i32_e32 vcc, v35, v252
	v_add_u32_e32 v35, 8, v34
	s_nop 0
	v_cndmask_b32_e32 v5, v220, v5, vcc
	v_cmp_le_i32_e32 vcc, v35, v252
	v_add_u32_e32 v35, 40, v34
	s_nop 0
	v_cndmask_b32_e32 v22, v220, v22, vcc
	v_cmp_le_i32_e32 vcc, v35, v252
	v_add_u32_e32 v35, 9, v34
	s_nop 0
	v_cndmask_b32_e32 v6, v220, v6, vcc
	v_cmp_le_i32_e32 vcc, v35, v252
	v_add_u32_e32 v35, 41, v34
	s_nop 0
	v_cndmask_b32_e32 v23, v220, v23, vcc
	v_cmp_le_i32_e32 vcc, v35, v252
	v_add_u32_e32 v35, 10, v34
	s_nop 0
	v_cndmask_b32_e32 v7, v220, v7, vcc
	v_cmp_le_i32_e32 vcc, v35, v252
	v_add_u32_e32 v35, 42, v34
	s_nop 0
	v_cndmask_b32_e32 v24, v220, v24, vcc
	v_cmp_le_i32_e32 vcc, v35, v252
	v_add_u32_e32 v35, 11, v34
	s_nop 0
	v_cndmask_b32_e32 v8, v220, v8, vcc
	v_cmp_le_i32_e32 vcc, v35, v252
	v_add_u32_e32 v35, 43, v34
	s_nop 0
	v_cndmask_b32_e32 v25, v220, v25, vcc
	v_cmp_le_i32_e32 vcc, v35, v252
	v_add_u32_e32 v35, 16, v34
	s_nop 0
	v_cndmask_b32_e32 v9, v220, v9, vcc
	v_cmp_le_i32_e32 vcc, v35, v252
	v_add_u32_e32 v35, 48, v34
	s_nop 0
	v_cndmask_b32_e32 v26, v220, v26, vcc
	v_cmp_le_i32_e32 vcc, v35, v252
	v_add_u32_e32 v35, 17, v34
	s_nop 0
	v_cndmask_b32_e32 v10, v220, v10, vcc
	v_cmp_le_i32_e32 vcc, v35, v252
	v_add_u32_e32 v35, 49, v34
	s_nop 0
	v_cndmask_b32_e32 v27, v220, v27, vcc
	v_cmp_le_i32_e32 vcc, v35, v252
	v_add_u32_e32 v35, 18, v34
	s_nop 0
	v_cndmask_b32_e32 v11, v220, v11, vcc
	v_cmp_le_i32_e32 vcc, v35, v252
	v_add_u32_e32 v35, 50, v34
	s_nop 0
	v_cndmask_b32_e32 v28, v220, v28, vcc
	v_cmp_le_i32_e32 vcc, v35, v252
	v_add_u32_e32 v35, 19, v34
	s_nop 0
	v_cndmask_b32_e32 v12, v220, v12, vcc
	v_cmp_le_i32_e32 vcc, v35, v252
	v_add_u32_e32 v35, 51, v34
	s_nop 0
	v_cndmask_b32_e32 v29, v220, v29, vcc
	v_cmp_le_i32_e32 vcc, v35, v252
	v_add_u32_e32 v35, 24, v34
	s_nop 0
	v_cndmask_b32_e32 v13, v220, v13, vcc
	v_cmp_le_i32_e32 vcc, v35, v252
	v_add_u32_e32 v35, 56, v34
	s_nop 0
	v_cndmask_b32_e32 v30, v220, v30, vcc
	v_cmp_le_i32_e32 vcc, v35, v252
	v_add_u32_e32 v35, 25, v34
	s_nop 0
	v_cndmask_b32_e32 v14, v220, v14, vcc
	v_cmp_le_i32_e32 vcc, v35, v252
	v_add_u32_e32 v35, 57, v34
	s_nop 0
	v_cndmask_b32_e32 v31, v220, v31, vcc
	v_cmp_le_i32_e32 vcc, v35, v252
	v_add_u32_e32 v35, 26, v34
	s_nop 0
	v_cndmask_b32_e32 v15, v220, v15, vcc
	v_cmp_le_i32_e32 vcc, v35, v252
	v_add_u32_e32 v35, 58, v34
	s_nop 0
	v_cndmask_b32_e32 v32, v220, v32, vcc
	v_cmp_le_i32_e32 vcc, v35, v252
	v_add_u32_e32 v35, 27, v34
	v_add_u32_e32 v34, 59, v34
	v_cndmask_b32_e32 v16, v220, v16, vcc
	v_cmp_le_i32_e32 vcc, v35, v252
	s_nop 1
	v_cndmask_b32_e32 v33, v220, v33, vcc
	v_cmp_le_i32_e32 vcc, v34, v252
	s_nop 1
	v_cndmask_b32_e32 v17, v220, v17, vcc

; #define MFMA32(a, b, c) __builtin_amdgcn_mfma_f32_32x32x16_bf16((a), (b), (c), 0, 0, 0)
; #define PV_IDX(g) (((g) & 1) * 4 + PV_KS(g))
; template <int DQK, int DV, bool MLA>
; __device__ __forceinline__ void attn_pass(LAS unsigned char* lds, const bf16_t* Qrow, const bf16_t* K0, int pitchK, const bf16_t* KrB, const bf16_t* Vt0, int NT, int q0w,
;                                           f32x16 (&o)[DV / 32], float& l_out, int tid) {
;     ...
;             __builtin_amdgcn_s_setprio(1);
; #pragma unroll
;             for (int d0 = 0; d0 < ND; ++d0) { s0 = MFMA32(kf[2 * d0], q[d0], s0); s1 = MFMA32(kf[2 * d0 + 1], q[d0], s1); }
;             __builtin_amdgcn_s_setprio(0);
;             __builtin_amdgcn_sched_barrier(0);
;             if (t + 1 < NT) ATT_KLOAD((t + 1) & 3);
;             bf16x8 vf[8];
;             if (pend) {
; #pragma unroll
;                 for (int g = 0; g < 8; ++g) vf[PV_IDX(g)] = VFRAG(vp, PV_D(g), PV_KS(g));
;             }
.LBB0_70:
	s_waitcnt lgkmcnt(0)
	v_mfma_f32_32x32x16_bf16 v[66:81], v[150:153], v[82:85], v[34:49]
	v_mfma_f32_32x32x16_bf16 v[50:65], v[146:149], v[82:85], v[34:49]
	v_mfma_f32_32x32x16_bf16 v[66:81], v[142:145], v[86:89], v[66:81]
	v_mfma_f32_32x32x16_bf16 v[50:65], v[138:141], v[86:89], v[50:65]
	v_mfma_f32_32x32x16_bf16 v[66:81], v[134:137], v[90:93], v[66:81]
	v_mfma_f32_32x32x16_bf16 v[50:65], v[130:133], v[90:93], v[50:65]
	v_mfma_f32_32x32x16_bf16 v[66:81], v[126:129], v[94:97], v[66:81]
	v_mfma_f32_32x32x16_bf16 v[50:65], v[122:125], v[94:97], v[50:65]
	v_mfma_f32_32x32x16_bf16 v[66:81], v[114:117], v[98:101], v[66:81]
	v_mfma_f32_32x32x16_bf16 v[50:65], v[110:113], v[98:101], v[50:65]
	v_mfma_f32_32x32x16_bf16 v[66:81], v[118:121], v[102:105], v[66:81]
	v_mfma_f32_32x32x16_bf16 v[50:65], v[106:109], v[102:105], v[50:65]
	v_add_u32_e32 v170, v214, v244
	v_add_u32_e32 v174, v214, v251
	v_add_u32_e32 v182, v214, v250
	v_add_u32_e32 v190, v214, v249
	ds_read_b128 v[178:181], v170 offset:49152
	ds_read_b128 v[170:173], v170 offset:53248
	ds_read_b128 v[186:189], v174 offset:49152
	ds_read_b128 v[174:177], v174 offset:53248
	ds_read_b128 v[194:197], v182 offset:49152
	ds_read_b128 v[182:185], v182 offset:53248
	ds_read_b128 v[198:201], v190 offset:49152
	ds_read_b128 v[190:193], v190 offset:53248
	s_add_i32 s6, s57, 5
	s_and_b32 s6, s6, 3
	v_lshl_add_u32 v106, s6, 13, v246
	v_add_u32_e32 v108, v106, v244
	ds_read_b128 v[150:153], v108
	ds_read_b128 v[146:149], v108 offset:4096
	v_add_u32_e32 v108, v106, v251
	v_lshl_add_u32 v107, s6, 12, v247
	ds_read_b128 v[142:145], v108
	ds_read_b128 v[138:141], v108 offset:4096
	v_add_u32_e32 v108, v106, v250
	v_add_u32_e32 v106, v106, v249
	ds_read_b128 v[134:137], v108
	ds_read_b128 v[130:133], v108 offset:4096
	ds_read_b128 v[126:129], v106
	ds_read_b128 v[122:125], v106 offset:4096
	v_add_u32_e32 v106, v107, v245
	v_add_u32_e32 v118, v107, v248
	ds_read_b128 v[114:117], v106 offset:32768
	ds_read_b128 v[110:113], v106 offset:34816
	ds_read_b128 v[106:109], v118 offset:34816
	ds_read_b128 v[118:121], v118 offset:32768

; template <int DQK, int DV, bool MLA>
; __device__ __forceinline__ void attn_pass(LAS unsigned char* lds, const bf16_t* Qrow, const bf16_t* K0, int pitchK, const bf16_t* KrB, const bf16_t* Vt0, int NT, int q0w,
;                                           f32x16 (&o)[DV / 32], float& l_out, int tid) {
;     ...
;     bf16x8 q[ND];
; #pragma unroll
;     for (int d0 = 0; d0 < ND; ++d0) q[d0] = *(const GAS bf16x8*)(Qrow + 16 * d0 + 8 * hi);
; #pragma unroll
;     for (int d = 0; d < NDV; ++d)
; #pragma unroll
;         for (int r = 0; r < 16; ++r) o[d][r] = 0.f;
;     float m = 0.f, l = 0.f;
;     f32x16 negm;
; #pragma unroll
;     for (int r = 0; r < 16; ++r) negm[r] = 0.f;
; #pragma unroll
;     for (int d0 = 0; d0 < ND; ++d0) asm volatile("" : "+v"(q[d0]));
;     const bf16_t* ksrc; const bf16_t* rsrc = nullptr; const bf16_t* vsrc[NVC];
;     { const int row = 8 * wid + (lane >> 3), c = (lane & 7) ^ ((row >> 1) & 7); ksrc = K0 + (size_t)row * pitchK + c * 8; }
;     if (MLA) { const int row = 16 * (wid & 3) + (lane >> 2), c = (lane & 3) ^ ((row >> 2) & 3); rsrc = KrB + (size_t)row * 32 + c * 8; }
; #pragma unroll
;     for (int j = 0; j < NVC; ++j) { const int row = 8 * (wid + 8 * j) + (lane >> 3), c = (lane & 7) ^ ((row >> 1) & 7); vsrc[j] = Vt0 + (size_t)row * 64 + c * 8; }
;     ...
;     const int xs = (r32 >> 1) & 7;
;     const int yk = (xs ^ hi) << 4;
;     const int yr = (((r32 >> 2) & 3) ^ hi) << 4;
;     bf16x8 kf[2 * ND];
;     ...
;     ATT_DMA_K(0, 0); ATT_DMA_V(0, 0); ATT_DMA_K(1, 1); ATT_DMA_V(1, 1); ATT_DMA_K(2, 2);
;     asm volatile("s_waitcnt vmcnt(0)" ::: "memory");
;     __builtin_amdgcn_s_barrier();
;     asm volatile("" ::: "memory");
;     ATT_KLOAD(0);
; __device__ __forceinline__ void attention_phase(const KP& p, LAS unsigned char* lds, unsigned char* ws, int rep) {
;     ...
;             const int b = w >> 2, h = w & 3; const size_t rb = (size_t)b * SEQ;
;             const bf16_t* Qd = (const bf16_t*)(ws + WS_QD); const bf16_t* Kd = (const bf16_t*)(ws + WS_KD); const bf16_t* Vt = (const bf16_t*)(ws + WS_VTD) + ((size_t)(b * (SEQ / 64)) * 512 + h * 128) * 64;
;             bf16_t* yo = ((bf16_t*)p.out) + (rb + q0w + r32) * 1024 + 512 + h * 128;
;             {
;                 f32x16 oA[4]; float lA;
;                 attn_pass<64, 128, false>(lds, Qd + (rb + q0w + r32) * 512 + (2 * h) * 64, Kd + rb * 512 + (2 * h) * 64, 512, nullptr, Vt, NT, q0w, oA, lA, tid);
.LBB0_92:
	s_and_b64 vcc, exec, s[6:7]
	s_cbranch_vccz .LBB0_45
	s_lshr_b32 s6, s53, 2
	s_lshl_b32 s7, s53, 7
	s_lshl_b32 s16, s6, 13
	s_lshl_b32 s6, s6, 23
	s_and_b32 s7, s7, 0x180
	s_add_u32 s14, s68, s6
	s_waitcnt lgkmcnt(3)
	v_lshl_add_u64 v[194:195], s[16:17], 0, v[202:203]
	s_addc_u32 s15, s69, 0
	s_lshl_b32 s44, s7, 7
	v_or_b32_e32 v194, v194, v242
	s_add_u32 s44, s14, s44
	v_lshlrev_b64 v[2:3], 10, v[194:195]
	s_addc_u32 s45, s15, 0
	v_lshl_add_u64 v[2:3], s[40:41], 0, v[2:3]
	s_lshl_b32 s16, s7, 1
	v_lshl_add_u64 v[2:3], v[2:3], 0, s[16:17]
	v_lshl_add_u64 v[196:197], v[2:3], 0, v[0:1]
	global_load_dwordx4 v[114:117], v[196:197], off
	s_waitcnt lgkmcnt(0)
	global_load_dwordx4 v[118:121], v[196:197], off offset:32
	global_load_dwordx4 v[122:125], v[196:197], off offset:64
	global_load_dwordx4 v[126:129], v[196:197], off offset:96
	s_add_u32 s6, s65, s6
	s_addc_u32 s14, s67, 0
	v_readfirstlane_b32 s7, v240
	s_add_u32 s48, s6, s16
	s_addc_u32 s49, s14, 0
	s_ashr_i32 s6, s7, 6
	v_lshl_or_b32 v2, s6, 3, v241
	v_lshrrev_b32_e32 v0, 1, v2
	v_ashrrev_i32_e32 v3, 31, v2
	v_xor_b32_e32 v0, v0, v240
	v_lshlrev_b64 v[4:5], 10, v[2:3]
	v_lshlrev_b32_e32 v0, 4, v0
	s_lshl_b32 s90, s6, 10
	v_lshlrev_b64 v[2:3], 7, v[2:3]
	v_lshl_add_u64 v[4:5], s[48:49], 0, v[4:5]
	v_and_b32_e32 v0, 0x70, v0
	s_add_i32 s90, s90, 0
	v_lshl_add_u64 v[2:3], s[44:45], 0, v[2:3]
	v_lshl_add_u64 v[50:51], v[4:5], 0, v[0:1]
	s_add_i32 s91, s90, 0x8000
	v_lshl_add_u64 v[52:53], v[2:3], 0, v[0:1]
	s_add_i32 s6, s90, 0xa000
	v_lshl_add_u64 v[54:55], v[52:53], 0, s[24:25]
	s_add_i32 s7, s90, 0x2000
	v_lshl_add_u64 v[2:3], v[50:51], 0, s[18:19]
	s_add_i32 s14, s90, 0xc000
	v_lshl_add_u64 v[4:5], v[52:53], 0, s[18:19]
	s_add_i32 s15, s90, 0xe000
	v_lshl_add_u64 v[6:7], v[52:53], 0, s[30:31]
	s_add_i32 s50, s90, 0x4000
	v_lshl_add_u64 v[8:9], v[50:51], 0, s[22:23]
	v_lshlrev_b32_e32 v210, 4, v243
	v_add_u32_e32 v211, 0, v238
	v_xor_b32_e32 v209, 32, v210
	v_xor_b32_e32 v208, 64, v210
	v_xor_b32_e32 v203, 0x60, v210
	s_cmp_gt_i32 s52, -1
	v_add_u32_e32 v213, v211, v203
	v_add_u32_e32 v214, v211, v208
	s_cselect_b64 s[46:47], -1, 0
	s_cmp_lt_i32 s52, 0
	v_add_u32_e32 v215, v211, v209
	v_add_u32_e32 v243, v211, v210
	v_or_b32_e32 v212, v202, v242
	v_cmp_lt_i32_e64 s[54:55], -1, v202
	s_mov_b32 s51, m0
	s_mov_b32 m0, s90
	s_nop 0
	global_load_lds_dwordx4 v[50:51], off
	s_mov_b32 m0, s51
	s_nop 0
	s_mov_b32 s51, m0
	s_mov_b32 m0, s91
	s_nop 0
	global_load_lds_dwordx4 v[52:53], off
	s_mov_b32 m0, s51
	s_nop 0
	s_mov_b32 s51, m0
	s_mov_b32 m0, s6
	s_nop 0
	global_load_lds_dwordx4 v[54:55], off
	s_mov_b32 m0, s51
	s_mov_b32 s6, m0
	s_mov_b32 m0, s7
	s_nop 0
	global_load_lds_dwordx4 v[2:3], off
	s_mov_b32 m0, s6
	s_nop 0
	s_mov_b32 s6, m0
	s_mov_b32 m0, s14
	s_nop 0
	global_load_lds_dwordx4 v[4:5], off
	s_mov_b32 m0, s6
	s_nop 0
	s_mov_b32 s6, m0
	s_mov_b32 m0, s15
	s_nop 0
	global_load_lds_dwordx4 v[6:7], off
	s_mov_b32 m0, s6
	s_nop 0
	s_mov_b32 s6, m0
	s_mov_b32 m0, s50
	s_nop 0
	global_load_lds_dwordx4 v[8:9], off
	s_mov_b32 m0, s6
	s_waitcnt vmcnt(0)
	s_barrier
	s_cbranch_scc1 .LBB0_167
	ds_read_b128 v[130:133], v213 offset:4096
	ds_read_b128 v[134:137], v213
	ds_read_b128 v[138:141], v214 offset:4096
	ds_read_b128 v[142:145], v214
	ds_read_b128 v[146:149], v215 offset:4096
	ds_read_b128 v[150:153], v215
	ds_read_b128 v[154:157], v243 offset:4096
	ds_read_b128 v[158:161], v243
	v_lshl_add_u64 v[2:3], v[50:51], 0, s[26:27]
	s_add_i32 s6, s90, 0x6000
	s_mov_b32 s7, m0
	s_mov_b32 m0, s6
	s_nop 0
	global_load_lds_dwordx4 v[2:3], off
	s_mov_b32 m0, s7
	v_lshl_add_u64 v[2:3], v[54:55], 0, s[22:23]
	v_lshl_add_u64 v[4:5], v[52:53], 0, s[22:23]
	s_add_i32 s6, s90, 0x10000
	s_mov_b32 s7, m0
	s_mov_b32 m0, s6
	s_nop 0
	global_load_lds_dwordx4 v[4:5], off
	s_mov_b32 m0, s7
	s_add_i32 s6, s90, 0x12000
	s_mov_b32 s7, m0
	s_mov_b32 m0, s6
	s_nop 0
	global_load_lds_dwordx4 v[2:3], off
	s_mov_b32 m0, s7
	v_mov_b32_e32 v2, v1
	v_mov_b32_e32 v3, v1
	v_mov_b32_e32 v4, v1
	v_mov_b32_e32 v5, v1
	v_mov_b32_e32 v6, v1
	v_mov_b32_e32 v7, v1
	v_mov_b32_e32 v8, v1
	v_mov_b32_e32 v9, v1
	v_mov_b32_e32 v10, v1
	v_mov_b32_e32 v11, v1
	v_mov_b32_e32 v12, v1
	v_mov_b32_e32 v13, v1
	v_mov_b32_e32 v14, v1
	v_mov_b32_e32 v15, v1
	v_mov_b32_e32 v0, v1
	v_mov_b64_e32 v[16:17], v[14:15]
	v_mov_b32_e32 v244, 0
	v_mov_b32_e32 v242, 0
	v_mov_b64_e32 v[14:15], v[12:13]
	v_mov_b64_e32 v[12:13], v[10:11]
	v_mov_b64_e32 v[10:11], v[8:9]
	v_mov_b64_e32 v[8:9], v[6:7]
	v_mov_b64_e32 v[6:7], v[4:5]
	v_mov_b64_e32 v[4:5], v[2:3]
	v_mov_b64_e32 v[2:3], v[0:1]
	s_and_saveexec_b64 s[50:51], s[54:55]
	s_cbranch_execz .LBB0_98
; #define MFMA32(a, b, c) __builtin_amdgcn_mfma_f32_32x32x16_bf16((a), (b), (c), 0, 0, 0)
; #define PV_IDX(g) (((g) & 1) * 4 + PV_KS(g))
; template <int DQK, int DV, bool MLA>
; __device__ __forceinline__ void attn_pass(LAS unsigned char* lds, const bf16_t* Qrow, const bf16_t* K0, int pitchK, const bf16_t* KrB, const bf16_t* Vt0, int NT, int q0w,
;                                           f32x16 (&o)[DV / 32], float& l_out, int tid) {
;     ...
;             __builtin_amdgcn_s_setprio(1);
; #pragma unroll
;             for (int d0 = 0; d0 < ND; ++d0) { s0 = MFMA32(kf[2 * d0], q[d0], s0); s1 = MFMA32(kf[2 * d0 + 1], q[d0], s1); }
;             __builtin_amdgcn_s_setprio(0);
;             __builtin_amdgcn_sched_barrier(0);
;             if (t + 1 < NT) ATT_KLOAD((t + 1) & 3);
;             bf16x8 vf[8];
;             if (pend) {
; #pragma unroll
;                 for (int g = 0; g < 8; ++g) vf[PV_IDX(g)] = VFRAG(vp, PV_D(g), PV_KS(g));
;             }
;             __builtin_amdgcn_sched_barrier(0);
;             if (64 * t + 63 > q0w) {
;                 int hi_l = hi; asm volatile("" : "+v"(hi_l));
;                 const int qrow = q0w + r32, kb0 = 64 * t + 4 * hi_l;
; #pragma unroll
;                 for (int r = 0; r < 16; ++r) { const int kv = kb0 + (r & 3) + 8 * (r >> 2); if (kv > qrow) s0[r] = -INFINITY; if (kv + 32 > qrow) s1[r] = -INFINITY; }
;             }
	s_waitcnt lgkmcnt(0)
	v_mfma_f32_32x32x16_bf16 v[34:49], v[158:161], v[114:117], 0
	v_mfma_f32_32x32x16_bf16 v[18:33], v[154:157], v[114:117], 0
	v_mfma_f32_32x32x16_bf16 v[34:49], v[150:153], v[118:121], v[34:49]
	v_mfma_f32_32x32x16_bf16 v[18:33], v[146:149], v[118:121], v[18:33]
	v_mfma_f32_32x32x16_bf16 v[34:49], v[142:145], v[122:125], v[34:49]
	v_mfma_f32_32x32x16_bf16 v[18:33], v[138:141], v[122:125], v[18:33]
	v_mfma_f32_32x32x16_bf16 v[34:49], v[134:137], v[126:129], v[34:49]
	v_mfma_f32_32x32x16_bf16 v[18:33], v[130:133], v[126:129], v[18:33]
	ds_read_b128 v[158:161], v243 offset:8192
	ds_read_b128 v[154:157], v243 offset:12288
	ds_read_b128 v[150:153], v215 offset:8192
	ds_read_b128 v[146:149], v215 offset:12288
	ds_read_b128 v[142:145], v214 offset:8192
	ds_read_b128 v[138:141], v214 offset:12288
	ds_read_b128 v[134:137], v213 offset:8192
	ds_read_b128 v[130:133], v213 offset:12288
	v_cmp_gt_u32_e32 vcc, 63, v202
	s_and_saveexec_b64 s[6:7], vcc
	s_cbranch_execz .LBB0_97
	v_mov_b32_e32 v0, v239
	s_nop 0
	v_lshlrev_b32_e32 v0, 2, v0
	v_add_u32_e32 v2, 32, v0
	v_cmp_le_i32_e32 vcc, v2, v212
	v_add_u32_e32 v2, 33, v0
	s_nop 0
	v_cndmask_b32_e32 v18, v220, v18, vcc
	v_cmp_lt_i32_e32 vcc, v0, v212
	s_nop 1
	v_cndmask_b32_e32 v35, v220, v35, vcc
	v_cmp_le_i32_e32 vcc, v0, v212
	s_nop 1
	v_cndmask_b32_e32 v34, v220, v34, vcc
	v_cmp_le_i32_e32 vcc, v2, v212
	v_or_b32_e32 v2, 2, v0
	s_nop 0
	v_cndmask_b32_e32 v19, v220, v19, vcc
	v_cmp_le_i32_e32 vcc, v2, v212
	v_add_u32_e32 v2, 34, v0
	s_nop 0
	v_cndmask_b32_e32 v36, v220, v36, vcc
	v_cmp_le_i32_e32 vcc, v2, v212
	v_or_b32_e32 v2, 3, v0
	s_nop 0
	v_cndmask_b32_e32 v20, v220, v20, vcc
	v_cmp_le_i32_e32 vcc, v2, v212
	v_add_u32_e32 v2, 35, v0
	s_nop 0
	v_cndmask_b32_e32 v37, v220, v37, vcc
	v_cmp_le_i32_e32 vcc, v2, v212
	v_add_u32_e32 v2, 8, v0
	s_nop 0
	v_cndmask_b32_e32 v21, v220, v21, vcc
	v_cmp_le_i32_e32 vcc, v2, v212
	v_add_u32_e32 v2, 40, v0
	s_nop 0
	v_cndmask_b32_e32 v38, v220, v38, vcc
	v_cmp_le_i32_e32 vcc, v2, v212
	v_add_u32_e32 v2, 9, v0
	s_nop 0
	v_cndmask_b32_e32 v22, v220, v22, vcc
	v_cmp_le_i32_e32 vcc, v2, v212
	v_add_u32_e32 v2, 41, v0
	s_nop 0
	v_cndmask_b32_e32 v39, v220, v39, vcc
	v_cmp_le_i32_e32 vcc, v2, v212
	v_add_u32_e32 v2, 10, v0
	s_nop 0
	v_cndmask_b32_e32 v23, v220, v23, vcc
	v_cmp_le_i32_e32 vcc, v2, v212
	v_add_u32_e32 v2, 42, v0
	s_nop 0
	v_cndmask_b32_e32 v40, v220, v40, vcc
	v_cmp_le_i32_e32 vcc, v2, v212
	v_add_u32_e32 v2, 11, v0
	s_nop 0
	v_cndmask_b32_e32 v24, v220, v24, vcc
	v_cmp_le_i32_e32 vcc, v2, v212
	v_add_u32_e32 v2, 43, v0
	s_nop 0
	v_cndmask_b32_e32 v41, v220, v41, vcc
	v_cmp_le_i32_e32 vcc, v2, v212
	v_add_u32_e32 v2, 16, v0
	s_nop 0
	v_cndmask_b32_e32 v25, v220, v25, vcc
	v_cmp_le_i32_e32 vcc, v2, v212
	v_add_u32_e32 v2, 48, v0
	s_nop 0
	v_cndmask_b32_e32 v42, v220, v42, vcc
	v_cmp_le_i32_e32 vcc, v2, v212
	v_add_u32_e32 v2, 17, v0
	s_nop 0
	v_cndmask_b32_e32 v26, v220, v26, vcc
	v_cmp_le_i32_e32 vcc, v2, v212
	v_add_u32_e32 v2, 49, v0
	s_nop 0
	v_cndmask_b32_e32 v43, v220, v43, vcc
	v_cmp_le_i32_e32 vcc, v2, v212
	v_add_u32_e32 v2, 18, v0
	s_nop 0
	v_cndmask_b32_e32 v27, v220, v27, vcc
	v_cmp_le_i32_e32 vcc, v2, v212
	v_add_u32_e32 v2, 50, v0
	s_nop 0
	v_cndmask_b32_e32 v44, v220, v44, vcc
	v_cmp_le_i32_e32 vcc, v2, v212
	v_add_u32_e32 v2, 19, v0
	s_nop 0
	v_cndmask_b32_e32 v28, v220, v28, vcc
	v_cmp_le_i32_e32 vcc, v2, v212
	v_add_u32_e32 v2, 51, v0
	s_nop 0
	v_cndmask_b32_e32 v45, v220, v45, vcc
	v_cmp_le_i32_e32 vcc, v2, v212
	v_add_u32_e32 v2, 24, v0
	s_nop 0
	v_cndmask_b32_e32 v29, v220, v29, vcc
	v_cmp_le_i32_e32 vcc, v2, v212
	v_add_u32_e32 v2, 56, v0
	s_nop 0
	v_cndmask_b32_e32 v46, v220, v46, vcc
	v_cmp_le_i32_e32 vcc, v2, v212
	v_add_u32_e32 v2, 25, v0
	s_nop 0
	v_cndmask_b32_e32 v30, v220, v30, vcc
	v_cmp_le_i32_e32 vcc, v2, v212
	v_add_u32_e32 v2, 57, v0
	s_nop 0
	v_cndmask_b32_e32 v47, v220, v47, vcc
	v_cmp_le_i32_e32 vcc, v2, v212
	v_add_u32_e32 v2, 26, v0
	s_nop 0
	v_cndmask_b32_e32 v31, v220, v31, vcc
	v_cmp_le_i32_e32 vcc, v2, v212
	v_add_u32_e32 v2, 58, v0
	s_nop 0
	v_cndmask_b32_e32 v48, v220, v48, vcc
	v_cmp_le_i32_e32 vcc, v2, v212
	v_add_u32_e32 v2, 27, v0
	v_add_u32_e32 v0, 59, v0
	v_cndmask_b32_e32 v32, v220, v32, vcc
	v_cmp_le_i32_e32 vcc, v2, v212
	s_nop 1
	v_cndmask_b32_e32 v49, v220, v49, vcc
	v_cmp_le_i32_e32 vcc, v0, v212
	s_nop 1
	v_cndmask_b32_e32 v33, v220, v33, vcc

; #define MFMA32(a, b, c) __builtin_amdgcn_mfma_f32_32x32x16_bf16((a), (b), (c), 0, 0, 0)
; template <int DQK, int DV, bool MLA>
; __device__ __forceinline__ void attn_pass(LAS unsigned char* lds, const bf16_t* Qrow, const bf16_t* K0, int pitchK, const bf16_t* KrB, const bf16_t* Vt0, int NT, int q0w,
;                                           f32x16 (&o)[DV / 32], float& l_out, int tid) {
;     ...
;             __builtin_amdgcn_s_setprio(1);
; #pragma unroll
;             for (int d0 = 0; d0 < ND; ++d0) { s0 = MFMA32(kf[2 * d0], q[d0], s0); s1 = MFMA32(kf[2 * d0 + 1], q[d0], s1); }
;             __builtin_amdgcn_s_setprio(0);
;             __builtin_amdgcn_sched_barrier(0);
;             if (t + 1 < NT) ATT_KLOAD((t + 1) & 3);
.LBB0_110:
	s_waitcnt lgkmcnt(0)
	v_mfma_f32_32x32x16_bf16 v[98:113], v[158:161], v[114:117], 0
	v_mfma_f32_32x32x16_bf16 v[82:97], v[154:157], v[114:117], 0
	v_mfma_f32_32x32x16_bf16 v[98:113], v[150:153], v[118:121], v[98:113]
	v_mfma_f32_32x32x16_bf16 v[82:97], v[146:149], v[118:121], v[82:97]
	v_mfma_f32_32x32x16_bf16 v[98:113], v[142:145], v[122:125], v[98:113]
	v_mfma_f32_32x32x16_bf16 v[82:97], v[138:141], v[122:125], v[82:97]
	v_mfma_f32_32x32x16_bf16 v[98:113], v[134:137], v[126:129], v[98:113]
	v_mfma_f32_32x32x16_bf16 v[82:97], v[130:133], v[126:129], v[82:97]
	s_add_i32 s6, s94, -2
	s_cmp_ge_i32 s6, s88
	s_cbranch_scc1 .LBB0_112
	s_and_b32 s6, s93, 0x6000
	v_add_u32_e32 v130, s6, v211
	v_add_u32_e32 v131, v130, v210
	ds_read_b128 v[158:161], v131
	ds_read_b128 v[154:157], v131 offset:4096
	v_add_u32_e32 v131, v130, v209
	ds_read_b128 v[150:153], v131
	ds_read_b128 v[146:149], v131 offset:4096
	v_add_u32_e32 v131, v130, v208
	v_add_u32_e32 v130, v130, v203
	ds_read_b128 v[142:145], v131
	ds_read_b128 v[138:141], v131 offset:4096
	ds_read_b128 v[134:137], v130
	ds_read_b128 v[130:133], v130 offset:4096

; template <int DQK, int DV, bool MLA>
; __device__ __forceinline__ void attn_pass(LAS unsigned char* lds, const bf16_t* Qrow, const bf16_t* K0, int pitchK, const bf16_t* KrB, const bf16_t* Vt0, int NT, int q0w,
;                                           f32x16 (&o)[DV / 32], float& l_out, int tid) {
;     ...
;     bf16x8 q[ND];
; #pragma unroll
;     for (int d0 = 0; d0 < ND; ++d0) q[d0] = *(const GAS bf16x8*)(Qrow + 16 * d0 + 8 * hi);
; #pragma unroll
;     for (int d = 0; d < NDV; ++d)
; #pragma unroll
;         for (int r = 0; r < 16; ++r) o[d][r] = 0.f;
;     float m = 0.f, l = 0.f;
;     f32x16 negm;
; #pragma unroll
;     for (int r = 0; r < 16; ++r) negm[r] = 0.f;
; #pragma unroll
;     for (int d0 = 0; d0 < ND; ++d0) asm volatile("" : "+v"(q[d0]));
;     const bf16_t* ksrc; const bf16_t* rsrc = nullptr; const bf16_t* vsrc[NVC];
;     { const int row = 8 * wid + (lane >> 3), c = (lane & 7) ^ ((row >> 1) & 7); ksrc = K0 + (size_t)row * pitchK + c * 8; }
;     if (MLA) { const int row = 16 * (wid & 3) + (lane >> 2), c = (lane & 3) ^ ((row >> 2) & 3); rsrc = KrB + (size_t)row * 32 + c * 8; }
; #pragma unroll
;     for (int j = 0; j < NVC; ++j) { const int row = 8 * (wid + 8 * j) + (lane >> 3), c = (lane & 7) ^ ((row >> 1) & 7); vsrc[j] = Vt0 + (size_t)row * 64 + c * 8; }
;     ...
;     const int xs = (r32 >> 1) & 7;
;     const int yk = (xs ^ hi) << 4;
;     const int yr = (((r32 >> 2) & 3) ^ hi) << 4;
;     bf16x8 kf[2 * ND];
;     ...
;     ATT_DMA_K(0, 0); ATT_DMA_V(0, 0); ATT_DMA_K(1, 1); ATT_DMA_V(1, 1); ATT_DMA_K(2, 2);
;     asm volatile("s_waitcnt vmcnt(0)" ::: "memory");
; __device__ __forceinline__ void attention_phase(const KP& p, LAS unsigned char* lds, unsigned char* ws, int rep) {
;     ...
;                 const float ia = 1.0f / lA;
; #pragma unroll
;                 for (int d = 0; d < 4; ++d)
; #pragma unroll
;                     for (int g = 0; g < 4; ++g) {
;                         u32x2 wv; wv.x = cvtpk(oA[d][4 * g] * ia, oA[d][4 * g + 1] * ia); wv.y = cvtpk(oA[d][4 * g + 2] * ia, oA[d][4 * g + 3] * ia);
;                         *(GAS u32x2*)(yo + 32 * d + 8 * g + 4 * hi) = wv;
;                     }
;             }
;             f32x16 oB[4]; float lB;
;             attn_pass<64, 128, false>(lds, Qd + (rb + q0w + r32) * 512 + (2 * h + 1) * 64, Kd + rb * 512 + (2 * h + 1) * 64, 512, nullptr, Vt, NT, q0w, oB, lB, tid);
.LBB0_130:
	s_or_b64 exec, exec, s[6:7]
	v_mov_b32_e32 v0, v242
	s_nop 1
	v_permlane32_swap_b32_e32 v242, v0
	v_add_f32_e32 v0, v242, v0
	v_div_scale_f32 v36, s[6:7], v0, v0, 1.0
	v_rcp_f32_e32 v37, v36
	v_lshlrev_b64 v[34:35], 11, v[194:195]
	v_lshl_add_u64 v[34:35], s[82:83], 0, v[34:35]
	v_lshl_add_u64 v[34:35], v[34:35], 0, s[16:17]
	v_fma_f32 v38, -v36, v37, 1.0
	v_fmac_f32_e32 v37, v38, v37
	v_div_scale_f32 v38, vcc, 1.0, v0, 1.0
	v_mul_f32_e32 v39, v38, v37
	v_fma_f32 v40, -v36, v39, v38
	v_fmac_f32_e32 v39, v40, v37
	v_fma_f32 v36, -v36, v39, v38
	v_div_fmas_f32 v36, v36, v37, v39
	v_div_fixup_f32 v36, v36, v0, 1.0
	v_lshlrev_b32_e32 v0, 3, v239
	v_lshl_add_u64 v[194:195], v[34:35], 0, v[0:1]
	v_pk_mul_f32 v[34:35], v[66:67], v[36:37] op_sel_hi:[1,0]
	v_pk_mul_f32 v[38:39], v[68:69], v[36:37] op_sel_hi:[1,0]
	v_cvt_pk_bf16_f32 v34, v34, v35
	v_cvt_pk_bf16_f32 v35, v38, v39
	s_waitcnt lgkmcnt(0)
	s_barrier
	global_store_dwordx2 v[194:195], v[34:35], off offset:1024
	v_pk_mul_f32 v[34:35], v[70:71], v[36:37] op_sel_hi:[1,0]
	v_pk_mul_f32 v[38:39], v[72:73], v[36:37] op_sel_hi:[1,0]
	v_cvt_pk_bf16_f32 v34, v34, v35
	v_cvt_pk_bf16_f32 v35, v38, v39
	global_store_dwordx2 v[194:195], v[34:35], off offset:1040
	v_pk_mul_f32 v[34:35], v[74:75], v[36:37] op_sel_hi:[1,0]
	v_pk_mul_f32 v[38:39], v[76:77], v[36:37] op_sel_hi:[1,0]
	v_cvt_pk_bf16_f32 v34, v34, v35
	v_cvt_pk_bf16_f32 v35, v38, v39
	global_store_dwordx2 v[194:195], v[34:35], off offset:1056
	v_pk_mul_f32 v[34:35], v[78:79], v[36:37] op_sel_hi:[1,0]
	v_pk_mul_f32 v[38:39], v[80:81], v[36:37] op_sel_hi:[1,0]
	v_cvt_pk_bf16_f32 v34, v34, v35
	v_cvt_pk_bf16_f32 v35, v38, v39
	global_store_dwordx2 v[194:195], v[34:35], off offset:1072
	v_pk_mul_f32 v[34:35], v[50:51], v[36:37] op_sel_hi:[1,0]
	v_pk_mul_f32 v[38:39], v[52:53], v[36:37] op_sel_hi:[1,0]
	v_pk_mul_f32 v[18:19], v[18:19], v[36:37] op_sel_hi:[1,0]
	v_pk_mul_f32 v[20:21], v[20:21], v[36:37] op_sel_hi:[1,0]
	v_pk_mul_f32 v[2:3], v[2:3], v[36:37] op_sel_hi:[1,0]
	v_pk_mul_f32 v[4:5], v[4:5], v[36:37] op_sel_hi:[1,0]
	v_cvt_pk_bf16_f32 v34, v34, v35
	v_cvt_pk_bf16_f32 v35, v38, v39
	v_cvt_pk_bf16_f32 v18, v18, v19
	v_cvt_pk_bf16_f32 v19, v20, v21
	v_cvt_pk_bf16_f32 v2, v2, v3
	v_cvt_pk_bf16_f32 v3, v4, v5
	global_store_dwordx2 v[194:195], v[34:35], off offset:1088
	v_pk_mul_f32 v[34:35], v[54:55], v[36:37] op_sel_hi:[1,0]
	v_pk_mul_f32 v[38:39], v[56:57], v[36:37] op_sel_hi:[1,0]
	global_store_dwordx2 v[194:195], v[18:19], off offset:1152
	v_pk_mul_f32 v[18:19], v[22:23], v[36:37] op_sel_hi:[1,0]
	v_pk_mul_f32 v[20:21], v[24:25], v[36:37] op_sel_hi:[1,0]
	global_store_dwordx2 v[194:195], v[2:3], off offset:1216
	v_pk_mul_f32 v[2:3], v[6:7], v[36:37] op_sel_hi:[1,0]
	v_pk_mul_f32 v[4:5], v[8:9], v[36:37] op_sel_hi:[1,0]
	v_cvt_pk_bf16_f32 v34, v34, v35
	v_cvt_pk_bf16_f32 v35, v38, v39
	v_cvt_pk_bf16_f32 v18, v18, v19
	v_cvt_pk_bf16_f32 v19, v20, v21
	v_cvt_pk_bf16_f32 v2, v2, v3
	v_cvt_pk_bf16_f32 v3, v4, v5
	global_store_dwordx2 v[194:195], v[34:35], off offset:1104
	v_pk_mul_f32 v[34:35], v[58:59], v[36:37] op_sel_hi:[1,0]
	v_pk_mul_f32 v[38:39], v[60:61], v[36:37] op_sel_hi:[1,0]
	global_store_dwordx2 v[194:195], v[18:19], off offset:1168
	v_pk_mul_f32 v[18:19], v[26:27], v[36:37] op_sel_hi:[1,0]
	v_pk_mul_f32 v[20:21], v[28:29], v[36:37] op_sel_hi:[1,0]
	global_store_dwordx2 v[194:195], v[2:3], off offset:1232
	v_pk_mul_f32 v[2:3], v[10:11], v[36:37] op_sel_hi:[1,0]
	v_pk_mul_f32 v[4:5], v[12:13], v[36:37] op_sel_hi:[1,0]
	v_cvt_pk_bf16_f32 v34, v34, v35
	v_cvt_pk_bf16_f32 v35, v38, v39
	v_cvt_pk_bf16_f32 v18, v18, v19
	v_cvt_pk_bf16_f32 v19, v20, v21
	v_cvt_pk_bf16_f32 v2, v2, v3
	v_cvt_pk_bf16_f32 v3, v4, v5
	global_store_dwordx2 v[194:195], v[34:35], off offset:1120
	v_pk_mul_f32 v[34:35], v[62:63], v[36:37] op_sel_hi:[1,0]
	v_pk_mul_f32 v[38:39], v[64:65], v[36:37] op_sel_hi:[1,0]
	global_store_dwordx2 v[194:195], v[18:19], off offset:1184
	v_pk_mul_f32 v[18:19], v[30:31], v[36:37] op_sel_hi:[1,0]
	v_pk_mul_f32 v[20:21], v[32:33], v[36:37] op_sel_hi:[1,0]
	global_store_dwordx2 v[194:195], v[2:3], off offset:1248
	v_pk_mul_f32 v[2:3], v[14:15], v[36:37] op_sel_hi:[1,0]
	v_pk_mul_f32 v[4:5], v[16:17], v[36:37] op_sel_hi:[1,0]
	v_cvt_pk_bf16_f32 v34, v34, v35
	v_cvt_pk_bf16_f32 v35, v38, v39
	v_cvt_pk_bf16_f32 v18, v18, v19
	v_cvt_pk_bf16_f32 v19, v20, v21
	v_cvt_pk_bf16_f32 v2, v2, v3
	v_cvt_pk_bf16_f32 v3, v4, v5
	global_store_dwordx2 v[194:195], v[34:35], off offset:1136
	global_store_dwordx2 v[194:195], v[18:19], off offset:1200
	global_store_dwordx2 v[194:195], v[2:3], off offset:1264
	global_load_dwordx4 v[114:117], v[196:197], off offset:128
	global_load_dwordx4 v[118:121], v[196:197], off offset:160
	global_load_dwordx4 v[122:125], v[196:197], off offset:192
	global_load_dwordx4 v[126:129], v[196:197], off offset:224
	v_readfirstlane_b32 s6, v240
	s_ashr_i32 s6, s6, 6
	s_lshl_b32 s16, s6, 10
	v_lshl_or_b32 v2, s6, 3, v241
	v_lshrrev_b32_e32 v0, 1, v2
	v_xor_b32_e32 v0, v0, v240
	v_ashrrev_i32_e32 v3, 31, v2
	v_lshlrev_b64 v[4:5], 10, v[2:3]
	v_lshlrev_b64 v[2:3], 7, v[2:3]
	v_lshlrev_b32_e32 v0, 4, v0
	v_lshl_add_u64 v[2:3], s[44:45], 0, v[2:3]
	v_and_b32_e32 v0, 0x70, v0
	v_lshl_add_u64 v[66:67], v[2:3], 0, v[0:1]
	v_lshl_add_u64 v[2:3], s[48:49], 0, v[4:5]
	v_lshl_add_u64 v[2:3], v[2:3], 0, v[0:1]
	v_lshl_add_u64 v[70:71], v[2:3], 0, s[34:35]
	s_add_i32 s16, s16, 0
	s_mov_b32 s6, m0
	s_mov_b32 m0, s16
	s_nop 0
	global_load_lds_dwordx4 v[70:71], off
	s_mov_b32 m0, s6
	s_add_i32 s52, s16, 0x8000
	s_mov_b32 s6, m0
	s_mov_b32 m0, s52
	s_nop 0
	global_load_lds_dwordx4 v[66:67], off
	s_mov_b32 m0, s6
	v_lshl_add_u64 v[68:69], v[66:67], 0, s[24:25]
	s_add_i32 s6, s16, 0xa000
	s_mov_b32 s7, m0
	s_mov_b32 m0, s6
	s_nop 0
	global_load_lds_dwordx4 v[68:69], off
	s_mov_b32 m0, s7
	s_mov_b64 s[6:7], 0x10080
	v_lshl_add_u64 v[4:5], v[2:3], 0, s[6:7]
	s_add_i32 s6, s16, 0x2000
	s_mov_b32 s7, m0
	s_mov_b32 m0, s6
	s_nop 0
	global_load_lds_dwordx4 v[4:5], off
	s_mov_b32 m0, s7
	v_lshl_add_u64 v[4:5], v[66:67], 0, s[18:19]
	s_add_i32 s6, s16, 0xc000
	s_mov_b32 s7, m0
	s_mov_b32 m0, s6
	s_nop 0
	global_load_lds_dwordx4 v[4:5], off
	s_mov_b32 m0, s7
	v_lshl_add_u64 v[4:5], v[66:67], 0, s[30:31]
	s_add_i32 s6, s16, 0xe000
	s_mov_b32 s7, m0
	s_mov_b32 m0, s6
	s_nop 0
	global_load_lds_dwordx4 v[4:5], off
	s_mov_b32 m0, s7
	s_mov_b64 s[6:7], 0x20080
	v_lshl_add_u64 v[2:3], v[2:3], 0, s[6:7]
	s_add_i32 s6, s16, 0x4000
	s_mov_b32 s7, m0
	s_mov_b32 m0, s6
	s_nop 0
	global_load_lds_dwordx4 v[2:3], off
	s_mov_b32 m0, s7
	s_waitcnt vmcnt(0)
	s_barrier
; #define LAS __attribute__((address_space(3)))
; #define MFMA32(a, b, c) __builtin_amdgcn_mfma_f32_32x32x16_bf16((a), (b), (c), 0, 0, 0)
; #define PV_IDX(g) (((g) & 1) * 4 + PV_KS(g))
; template <int DQK, int DV, bool MLA>
; __device__ __forceinline__ void attn_pass(LAS unsigned char* lds, const bf16_t* Qrow, const bf16_t* K0, int pitchK, const bf16_t* KrB, const bf16_t* Vt0, int NT, int q0w,
;                                           f32x16 (&o)[DV / 32], float& l_out, int tid) {
;     ...
;     ATT_DMA_K(0, 0); ATT_DMA_V(0, 0); ATT_DMA_K(1, 1); ATT_DMA_V(1, 1); ATT_DMA_K(2, 2);
;     asm volatile("s_waitcnt vmcnt(0)" ::: "memory");
;     __builtin_amdgcn_s_barrier();
;     asm volatile("" ::: "memory");
;     ATT_KLOAD(0);
;     bf16x8 pf[4];
;     bool pend = false;
;     int vs_prev = 0;
;     ...
;     for (int t = 0; t < NT; ++t) {
;         const bool far = t + 3 < NT;
;         if (far) ATT_DMA_K(t + 3, (t + 3) & 3);
;         if (t + 2 < NT) ATT_DMA_V(t + 2, (t + 2) & 3);
;         const LAS unsigned char* vp = lds + VOFF + vs_prev * VB + r32 * 128;
;         if (64 * t <= q0w + 31) {
;             f32x16 s0, s1;
;             if constexpr (MLA) { s0 = negm; s1 = negm; }
;             else {
; #pragma unroll
;                 for (int r = 0; r < 16; ++r) { s0[r] = 0.f; s1[r] = 0.f; }
;             }
;             __builtin_amdgcn_s_setprio(1);
; #pragma unroll
;             for (int d0 = 0; d0 < ND; ++d0) { s0 = MFMA32(kf[2 * d0], q[d0], s0); s1 = MFMA32(kf[2 * d0 + 1], q[d0], s1); }
;             __builtin_amdgcn_s_setprio(0);
;             __builtin_amdgcn_sched_barrier(0);
;             if (t + 1 < NT) ATT_KLOAD((t + 1) & 3);
;             bf16x8 vf[8];
;             if (pend) {
; #pragma unroll
;                 for (int g = 0; g < 8; ++g) vf[PV_IDX(g)] = VFRAG(vp, PV_D(g), PV_KS(g));
;             }
;             __builtin_amdgcn_sched_barrier(0);
;             if (64 * t + 63 > q0w) {
;                 int hi_l = hi; asm volatile("" : "+v"(hi_l));
;                 const int qrow = q0w + r32, kb0 = 64 * t + 4 * hi_l;
; #pragma unroll
;                 for (int r = 0; r < 16; ++r) { const int kv = kb0 + (r & 3) + 8 * (r >> 2); if (kv > qrow) s0[r] = -INFINITY; if (kv + 32 > qrow) s1[r] = -INFINITY; }
;             }
	s_andn2_b64 vcc, exec, s[46:47]
	s_cbranch_vccnz .LBB0_168
	s_waitcnt lgkmcnt(0)
	ds_read_b128 v[130:133], v213 offset:4096
	ds_read_b128 v[134:137], v213
	ds_read_b128 v[138:141], v214 offset:4096
	ds_read_b128 v[142:145], v214
	ds_read_b128 v[146:149], v215 offset:4096
	ds_read_b128 v[150:153], v215
	ds_read_b128 v[154:157], v243 offset:4096
	ds_read_b128 v[158:161], v243
	v_lshl_add_u64 v[2:3], v[70:71], 0, s[26:27]
	s_add_i32 s6, s16, 0x6000
	s_mov_b32 s7, m0
	s_mov_b32 m0, s6
	s_nop 0
	global_load_lds_dwordx4 v[2:3], off
	s_mov_b32 m0, s7
	v_lshl_add_u64 v[2:3], v[68:69], 0, s[22:23]
	v_lshl_add_u64 v[4:5], v[66:67], 0, s[22:23]
	s_add_i32 s6, s16, 0x10000
	s_mov_b32 s7, m0
	s_mov_b32 m0, s6
	s_nop 0
	global_load_lds_dwordx4 v[4:5], off
	s_mov_b32 m0, s7
	s_add_i32 s6, s16, 0x12000
	s_mov_b32 s7, m0
	s_mov_b32 m0, s6
	s_nop 0
	global_load_lds_dwordx4 v[2:3], off
	s_mov_b32 m0, s7
	v_mov_b32_e32 v2, v1
	v_mov_b32_e32 v3, v1
	v_mov_b32_e32 v4, v1
	v_mov_b32_e32 v5, v1
	v_mov_b32_e32 v6, v1
	v_mov_b32_e32 v7, v1
	v_mov_b32_e32 v8, v1
	v_mov_b32_e32 v9, v1
	v_mov_b32_e32 v10, v1
	v_mov_b32_e32 v11, v1
	v_mov_b32_e32 v12, v1
	v_mov_b32_e32 v13, v1
	v_mov_b32_e32 v14, v1
	v_mov_b32_e32 v15, v1
	v_mov_b32_e32 v0, v1
	v_mov_b64_e32 v[16:17], v[14:15]
	v_cmp_lt_i32_e64 s[48:49], -1, v202
	v_mov_b32_e32 v207, 0
	v_mov_b32_e32 v206, 0
	v_mov_b64_e32 v[14:15], v[12:13]
	v_mov_b64_e32 v[12:13], v[10:11]
	v_mov_b64_e32 v[10:11], v[8:9]
	v_mov_b64_e32 v[8:9], v[6:7]
	v_mov_b64_e32 v[6:7], v[4:5]
	v_mov_b64_e32 v[4:5], v[2:3]
	v_mov_b64_e32 v[2:3], v[0:1]
	s_and_saveexec_b64 s[44:45], s[48:49]
	s_cbranch_execz .LBB0_135
	s_waitcnt lgkmcnt(0)
	v_mfma_f32_32x32x16_bf16 v[34:49], v[158:161], v[114:117], 0
	v_mfma_f32_32x32x16_bf16 v[18:33], v[154:157], v[114:117], 0
	v_mfma_f32_32x32x16_bf16 v[34:49], v[150:153], v[118:121], v[34:49]
	v_mfma_f32_32x32x16_bf16 v[18:33], v[146:149], v[118:121], v[18:33]
	v_mfma_f32_32x32x16_bf16 v[34:49], v[142:145], v[122:125], v[34:49]
	v_mfma_f32_32x32x16_bf16 v[18:33], v[138:141], v[122:125], v[18:33]
	v_mfma_f32_32x32x16_bf16 v[34:49], v[134:137], v[126:129], v[34:49]
	v_mfma_f32_32x32x16_bf16 v[18:33], v[130:133], v[126:129], v[18:33]
	ds_read_b128 v[158:161], v243 offset:8192
	ds_read_b128 v[154:157], v243 offset:12288
	ds_read_b128 v[150:153], v215 offset:8192
	ds_read_b128 v[146:149], v215 offset:12288
	ds_read_b128 v[142:145], v214 offset:8192
	ds_read_b128 v[138:141], v214 offset:12288
	ds_read_b128 v[134:137], v213 offset:8192
	ds_read_b128 v[130:133], v213 offset:12288
	v_cmp_gt_u32_e32 vcc, 63, v202
	s_and_saveexec_b64 s[6:7], vcc
	s_cbranch_execz .LBB0_134
	v_mov_b32_e32 v0, v239
	s_nop 0
	v_lshlrev_b32_e32 v0, 2, v0
	v_add_u32_e32 v2, 32, v0
	v_cmp_le_i32_e32 vcc, v2, v212
	v_add_u32_e32 v2, 33, v0
	s_nop 0
	v_cndmask_b32_e32 v18, v220, v18, vcc
	v_cmp_lt_i32_e32 vcc, v0, v212
	s_nop 1
	v_cndmask_b32_e32 v35, v220, v35, vcc
	v_cmp_le_i32_e32 vcc, v0, v212
	s_nop 1
	v_cndmask_b32_e32 v34, v220, v34, vcc
	v_cmp_le_i32_e32 vcc, v2, v212
	v_or_b32_e32 v2, 2, v0
	s_nop 0
	v_cndmask_b32_e32 v19, v220, v19, vcc
	v_cmp_le_i32_e32 vcc, v2, v212
	v_add_u32_e32 v2, 34, v0
	s_nop 0
	v_cndmask_b32_e32 v36, v220, v36, vcc
	v_cmp_le_i32_e32 vcc, v2, v212
	v_or_b32_e32 v2, 3, v0
	s_nop 0
	v_cndmask_b32_e32 v20, v220, v20, vcc
	v_cmp_le_i32_e32 vcc, v2, v212
	v_add_u32_e32 v2, 35, v0
	s_nop 0
	v_cndmask_b32_e32 v37, v220, v37, vcc
	v_cmp_le_i32_e32 vcc, v2, v212
	v_add_u32_e32 v2, 8, v0
	s_nop 0
	v_cndmask_b32_e32 v21, v220, v21, vcc
	v_cmp_le_i32_e32 vcc, v2, v212
	v_add_u32_e32 v2, 40, v0
	s_nop 0
	v_cndmask_b32_e32 v38, v220, v38, vcc
	v_cmp_le_i32_e32 vcc, v2, v212
	v_add_u32_e32 v2, 9, v0
	s_nop 0
	v_cndmask_b32_e32 v22, v220, v22, vcc
	v_cmp_le_i32_e32 vcc, v2, v212
	v_add_u32_e32 v2, 41, v0
	s_nop 0
	v_cndmask_b32_e32 v39, v220, v39, vcc
	v_cmp_le_i32_e32 vcc, v2, v212
	v_add_u32_e32 v2, 10, v0
	s_nop 0
	v_cndmask_b32_e32 v23, v220, v23, vcc
	v_cmp_le_i32_e32 vcc, v2, v212
	v_add_u32_e32 v2, 42, v0
	s_nop 0
	v_cndmask_b32_e32 v40, v220, v40, vcc
	v_cmp_le_i32_e32 vcc, v2, v212
	v_add_u32_e32 v2, 11, v0
	s_nop 0
	v_cndmask_b32_e32 v24, v220, v24, vcc
	v_cmp_le_i32_e32 vcc, v2, v212
	v_add_u32_e32 v2, 43, v0
	s_nop 0
	v_cndmask_b32_e32 v41, v220, v41, vcc
	v_cmp_le_i32_e32 vcc, v2, v212
	v_add_u32_e32 v2, 16, v0
	s_nop 0
	v_cndmask_b32_e32 v25, v220, v25, vcc
	v_cmp_le_i32_e32 vcc, v2, v212
	v_add_u32_e32 v2, 48, v0
	s_nop 0
	v_cndmask_b32_e32 v42, v220, v42, vcc
	v_cmp_le_i32_e32 vcc, v2, v212
	v_add_u32_e32 v2, 17, v0
	s_nop 0
	v_cndmask_b32_e32 v26, v220, v26, vcc
	v_cmp_le_i32_e32 vcc, v2, v212
	v_add_u32_e32 v2, 49, v0
	s_nop 0
	v_cndmask_b32_e32 v43, v220, v43, vcc
	v_cmp_le_i32_e32 vcc, v2, v212
	v_add_u32_e32 v2, 18, v0
	s_nop 0
	v_cndmask_b32_e32 v27, v220, v27, vcc
	v_cmp_le_i32_e32 vcc, v2, v212
	v_add_u32_e32 v2, 50, v0
	s_nop 0
	v_cndmask_b32_e32 v44, v220, v44, vcc
	v_cmp_le_i32_e32 vcc, v2, v212
	v_add_u32_e32 v2, 19, v0
	s_nop 0
	v_cndmask_b32_e32 v28, v220, v28, vcc
	v_cmp_le_i32_e32 vcc, v2, v212
	v_add_u32_e32 v2, 51, v0
	s_nop 0
	v_cndmask_b32_e32 v45, v220, v45, vcc
	v_cmp_le_i32_e32 vcc, v2, v212
	v_add_u32_e32 v2, 24, v0
	s_nop 0
	v_cndmask_b32_e32 v29, v220, v29, vcc
	v_cmp_le_i32_e32 vcc, v2, v212
	v_add_u32_e32 v2, 56, v0
	s_nop 0
	v_cndmask_b32_e32 v46, v220, v46, vcc
	v_cmp_le_i32_e32 vcc, v2, v212
	v_add_u32_e32 v2, 25, v0
	s_nop 0
	v_cndmask_b32_e32 v30, v220, v30, vcc
	v_cmp_le_i32_e32 vcc, v2, v212
	v_add_u32_e32 v2, 57, v0
	s_nop 0
	v_cndmask_b32_e32 v47, v220, v47, vcc
	v_cmp_le_i32_e32 vcc, v2, v212
	v_add_u32_e32 v2, 26, v0
	s_nop 0
	v_cndmask_b32_e32 v31, v220, v31, vcc
	v_cmp_le_i32_e32 vcc, v2, v212
	v_add_u32_e32 v2, 58, v0
	s_nop 0
	v_cndmask_b32_e32 v48, v220, v48, vcc
	v_cmp_le_i32_e32 vcc, v2, v212
	v_add_u32_e32 v2, 27, v0
	v_add_u32_e32 v0, 59, v0
	v_cndmask_b32_e32 v32, v220, v32, vcc
	v_cmp_le_i32_e32 vcc, v2, v212
	s_nop 1
	v_cndmask_b32_e32 v49, v220, v49, vcc
	v_cmp_le_i32_e32 vcc, v0, v212
	s_nop 1
	v_cndmask_b32_e32 v33, v220, v33, vcc

; #define MFMA32(a, b, c) __builtin_amdgcn_mfma_f32_32x32x16_bf16((a), (b), (c), 0, 0, 0)
; template <int DQK, int DV, bool MLA>
; __device__ __forceinline__ void attn_pass(LAS unsigned char* lds, const bf16_t* Qrow, const bf16_t* K0, int pitchK, const bf16_t* KrB, const bf16_t* Vt0, int NT, int q0w,
;                                           f32x16 (&o)[DV / 32], float& l_out, int tid) {
;     ...
;             __builtin_amdgcn_s_setprio(1);
; #pragma unroll
;             for (int d0 = 0; d0 < ND; ++d0) { s0 = MFMA32(kf[2 * d0], q[d0], s0); s1 = MFMA32(kf[2 * d0 + 1], q[d0], s1); }
;             __builtin_amdgcn_s_setprio(0);
;             __builtin_amdgcn_sched_barrier(0);
;             if (t + 1 < NT) ATT_KLOAD((t + 1) & 3);
.LBB0_147:
	s_waitcnt lgkmcnt(0)
	v_mfma_f32_32x32x16_bf16 v[98:113], v[158:161], v[114:117], 0
	v_mfma_f32_32x32x16_bf16 v[82:97], v[154:157], v[114:117], 0
	v_mfma_f32_32x32x16_bf16 v[98:113], v[150:153], v[118:121], v[98:113]
	v_mfma_f32_32x32x16_bf16 v[82:97], v[146:149], v[118:121], v[82:97]
	v_mfma_f32_32x32x16_bf16 v[98:113], v[142:145], v[122:125], v[98:113]
	v_mfma_f32_32x32x16_bf16 v[82:97], v[138:141], v[122:125], v[82:97]
	v_mfma_f32_32x32x16_bf16 v[98:113], v[134:137], v[126:129], v[98:113]
	v_mfma_f32_32x32x16_bf16 v[82:97], v[130:133], v[126:129], v[82:97]
	s_add_i32 s6, s55, -2
	s_cmp_ge_i32 s6, s88
	s_cbranch_scc1 .LBB0_149
	s_and_b32 s6, s54, 0x6000
	v_add_u32_e32 v130, s6, v211
	v_add_u32_e32 v131, v130, v210
	ds_read_b128 v[158:161], v131
	ds_read_b128 v[154:157], v131 offset:4096
	v_add_u32_e32 v131, v130, v209
	ds_read_b128 v[150:153], v131
	ds_read_b128 v[146:149], v131 offset:4096
	v_add_u32_e32 v131, v130, v208
	v_add_u32_e32 v130, v130, v203
	ds_read_b128 v[142:145], v131
	ds_read_b128 v[138:141], v131 offset:4096
	ds_read_b128 v[134:137], v130
	ds_read_b128 v[130:133], v130 offset:4096

; template <bool COOP>
; __global__ void __launch_bounds__(512) fwd(KP p, int step_lo, int step_hi) {
;     ...
;         const int kind = st == 0 ? ST_PRO : st == 8 ? ST_ATT : st == 14 ? ST_FIN : ST_GEMM;
;         const int job = st < 8 ? st - 1 : st - 2;
;     ...
;         if (kind == ST_PRO) prologue(p, lds, ws);
;         else
;     ...
;         if (kind == ST_ATT) attention_phase(p, lds, ws, rep);
;         else
;     ...
;         if (kind == ST_FIN) final_phase(p, ws);
.LBB0_169:
	s_setprio 0
	v_readlane_b32 s56, v254, 60
	v_readlane_b32 s58, v255, 3
	s_mov_b32 s68, 0x6dc9c883
	s_mov_b64 s[6:7], 0
	v_readlane_b32 s57, v254, 61
	v_readlane_b32 s59, v255, 4
	v_readlane_b32 s64, v254, 62
	s_mov_b32 s69, 0x3fc45f30
	s_movk_i32 s65, 0x7fff
	s_mov_b32 s70, 0x2aaaaaab
	v_readlane_b32 s71, v255, 5
